# rstd LDS stash in both epilogues; dead address arithmetic removed from the gate/up hit path
# speedup vs baseline: 1.0088x; 1.0038x over previous
; __device__ __forceinline__ unsigned pk_bf16(float lo, float hi) { f32x2e v = {lo, hi}; bf16x2e b = __builtin_convertvector(v, bf16x2e); return __builtin_bit_cast(unsigned, b); }
; __device__ __forceinline__ float silu_mul(float g, float u) { return g * __builtin_amdgcn_rcpf(1.0f + __builtin_amdgcn_exp2f(-1.4426950408889634f * g)) * u; }
;     __device__ __forceinline__ void operator()(const f32x4 (&acc)[2][2][4][2], const Unit& u, int wr, int wc, int fr, int fq) const {
;     ...
;         float rsa[2][4]; tile_rstd(rsa, ss, u.pm * BM, wr, fr, fq);
; #pragma unroll
;         for (int ai = 0; ai < 2; ++ai)
; #pragma unroll
;             for (int m = 0; m < 4; ++m) { bf16_t* rowp = O + (size_t)(row0 + ai * HALF + m * 16) * ldc + col0;
;                 const float rs = rsa[ai][m];
;                 const f32x4 g0 = acc[ai][0][m][0] * rs, g1 = acc[ai][0][m][1] * rs, u0 = acc[ai][1][m][0] * rs, u1 = acc[ai][1][m][1] * rs;
;                 u32x4 w; w.x = pk_bf16(silu_mul(g0[0], u0[0]), silu_mul(g0[1], u0[1])); w.y = pk_bf16(silu_mul(g0[2], u0[2]), silu_mul(g0[3], u0[3]));
;                 w.z = pk_bf16(silu_mul(g1[0], u1[0]), silu_mul(g1[1], u1[1])); w.w = pk_bf16(silu_mul(g1[2], u1[2]), silu_mul(g1[3], u1[3]));
;                 *(u32x4*)rowp = w; }
.Lswi_hit:
	v_lshrrev_b32_e32 v236, 6, v216
	v_and_b32_e32 v237, 15, v216
	v_lshlrev_b32_e32 v236, 9, v236
	v_lshl_add_u32 v236, v237, 5, v236
	v_add_u32_e32 v236, 0x21000, v236
	v_mov_b32_e32 v237, s6
	v_add_u32_e32 v237, 1, v237
	s_lshl_b32 s0, s6, 8
	s_add_i32 s0, s0, s73
	v_or_b32_e32 v130, s0, v206
	v_add_u32_e32 v130, 0xb0, v130
	v_ashrrev_i32_e32 v131, 31, v130
	v_lshlrev_b64 v[130:131], 7, v[130:131]
	v_lshl_add_u64 v[130:131], v[184:185], 0, v[130:131]
	s_nop 0
	v_and_b32_e32 v192, 64, v220
	v_xor_b32_e32 v191, 1, v220
	v_add_u32_e32 v192, 64, v192
	v_cmp_lt_i32_e32 vcc, v191, v192
	v_or_b32_e32 v210, s0, v193
	v_readlane_b32 s0, v254, 63
	v_cndmask_b32_e32 v191, v220, v191, vcc
	v_lshlrev_b32_e32 v212, 2, v191
	v_xor_b32_e32 v191, 2, v220
	v_cmp_lt_i32_e32 vcc, v191, v192
	v_lshl_or_b32 v190, s2, 7, v208
	v_readlane_b32 s1, v255, 0
	v_cndmask_b32_e32 v191, v220, v191, vcc
	v_lshlrev_b32_e32 v211, 2, v191
	s_movk_i32 s2, 0x2c00
	s_waitcnt vmcnt(0) lgkmcnt(0)
	s_nop 0
	s_nop 0
	s_waitcnt lgkmcnt(0)
	s_waitcnt lgkmcnt(0)
	v_mov_b64_e32 v[204:205], s[24:25]
	s_nop 0
	s_nop 0
	ds_read_b32 v202, v236
	s_waitcnt lgkmcnt(0)
	v_pk_mul_f32 v[126:127], v[126:127], v[202:203] op_sel_hi:[1,0]
	v_pk_mul_f32 v[118:119], v[118:119], v[202:203] op_sel_hi:[1,0]
	v_pk_mul_f32 v[140:141], v[116:117], v[202:203] op_sel_hi:[1,0]
	v_pk_mul_f32 v[116:117], v[114:115], v[202:203] op_sel_hi:[1,0]
	v_mul_f32_e32 v114, 0xbfb8aa3b, v126
	v_mul_f32_e32 v115, 0xbfb8aa3b, v127
	v_exp_f32_e32 v114, v114
	v_exp_f32_e32 v115, v115
	v_pk_mul_f32 v[128:129], v[128:129], v[202:203] op_sel_hi:[1,0]
	v_add_f32_e32 v114, 1.0, v114
	v_add_f32_e32 v115, 1.0, v115
	v_rcp_f32_e32 v114, v114
	v_rcp_f32_e32 v115, v115
	s_nop 0
	v_pk_mul_f32 v[114:115], v[126:127], v[114:115]
	v_pk_mul_f32 v[114:115], v[118:119], v[114:115]
	v_cvt_pk_bf16_f32 v114, v114, v115
	v_mul_f32_e32 v115, 0xbfb8aa3b, v128
	v_exp_f32_e32 v115, v115
	s_nop 0
	v_add_f32_e32 v115, 1.0, v115
	v_rcp_f32_e32 v118, v115
	v_mul_f32_e32 v115, 0xbfb8aa3b, v129
	v_exp_f32_e32 v115, v115
	s_waitcnt lgkmcnt(0)
	v_add_f32_e32 v115, 1.0, v115
	v_rcp_f32_e32 v119, v115
	s_waitcnt lgkmcnt(0)
	s_waitcnt lgkmcnt(0)
	v_pk_mul_f32 v[120:121], v[120:121], v[202:203] op_sel_hi:[1,0]
	v_pk_mul_f32 v[118:119], v[128:129], v[118:119]
	v_pk_mul_f32 v[122:123], v[122:123], v[202:203] op_sel_hi:[1,0]
	v_pk_mul_f32 v[118:119], v[120:121], v[118:119]
	v_cvt_pk_bf16_f32 v115, v118, v119
	v_mul_f32_e32 v118, 0xbfb8aa3b, v122
	v_mul_f32_e32 v119, 0xbfb8aa3b, v123
	v_exp_f32_e32 v118, v118
	v_exp_f32_e32 v119, v119
	s_waitcnt lgkmcnt(0)
	s_waitcnt lgkmcnt(0)
	v_add_f32_e32 v118, 1.0, v118
	v_add_f32_e32 v119, 1.0, v119
	ds_read_b32 v164, v236 offset:4
	v_rcp_f32_e32 v118, v118
	v_rcp_f32_e32 v119, v119
	s_waitcnt lgkmcnt(0)
	v_pk_mul_f32 v[118:119], v[122:123], v[118:119]
	v_pk_mul_f32 v[124:125], v[124:125], v[202:203] op_sel_hi:[1,0]
	v_pk_mul_f32 v[116:117], v[116:117], v[118:119]
	v_cvt_pk_bf16_f32 v116, v116, v117
	v_mul_f32_e32 v117, 0xbfb8aa3b, v124
	ds_read_b32 v148, v236 offset:8
	v_exp_f32_e32 v117, v117
	s_nop 0
	v_add_f32_e32 v117, 1.0, v117
	v_rcp_f32_e32 v118, v117
	v_mul_f32_e32 v117, 0xbfb8aa3b, v125
	v_exp_f32_e32 v117, v117
	ds_read_b32 v136, v236 offset:12
	v_add_f32_e32 v117, 1.0, v117
	v_rcp_f32_e32 v119, v117
	ds_read_b32 v192, v236 offset:16
	ds_read_b32 v162, v236 offset:20
	ds_read_b32 v146, v236 offset:24
	ds_read_b32 v130, v236 offset:28
	v_ashrrev_i32_e32 v191, 31, v190
	v_mov_b64_e32 v[132:133], s[0:1]
	v_pk_mul_f32 v[118:119], v[124:125], v[118:119]
	v_mad_i64_i32 v[138:139], s[0:1], v210, s2, v[132:133]
	v_lshlrev_b64 v[134:135], 1, v[190:191]
	v_pk_mul_f32 v[118:119], v[140:141], v[118:119]
	v_lshl_add_u64 v[138:139], v[138:139], 0, v[134:135]
	v_cvt_pk_bf16_f32 v117, v118, v119
	s_waitcnt lgkmcnt(0)
	v_pk_mul_f32 v[110:111], v[110:111], v[192:193] op_sel_hi:[1,0]
	global_store_dwordx4 v[138:139], v[114:117], off
	v_pk_mul_f32 v[102:103], v[102:103], v[192:193] op_sel_hi:[1,0]
	v_pk_mul_f32 v[112:113], v[112:113], v[192:193] op_sel_hi:[1,0]
	v_pk_mul_f32 v[116:117], v[100:101], v[192:193] op_sel_hi:[1,0]
	v_pk_mul_f32 v[100:101], v[98:99], v[192:193] op_sel_hi:[1,0]
	v_mul_f32_e32 v98, 0xbfb8aa3b, v110
	v_mul_f32_e32 v99, 0xbfb8aa3b, v111
	v_exp_f32_e32 v98, v98
	v_exp_f32_e32 v99, v99
	v_pk_mul_f32 v[104:105], v[104:105], v[192:193] op_sel_hi:[1,0]
	v_pk_mul_f32 v[106:107], v[106:107], v[192:193] op_sel_hi:[1,0]
	v_add_f32_e32 v98, 1.0, v98
	v_add_f32_e32 v99, 1.0, v99
	v_rcp_f32_e32 v98, v98
	v_rcp_f32_e32 v99, v99
	v_pk_mul_f32 v[108:109], v[108:109], v[192:193] op_sel_hi:[1,0]
	v_or_b32_e32 v114, 16, v210
	v_mad_i64_i32 v[114:115], s[0:1], v114, s2, v[132:133]
	v_pk_mul_f32 v[98:99], v[110:111], v[98:99]
	v_lshl_add_u64 v[114:115], v[114:115], 0, v[134:135]
	v_pk_mul_f32 v[98:99], v[102:103], v[98:99]
	v_pk_mul_f32 v[92:93], v[92:93], v[164:165] op_sel_hi:[1,0]
	v_cvt_pk_bf16_f32 v98, v98, v99
	v_mul_f32_e32 v99, 0xbfb8aa3b, v112
	v_exp_f32_e32 v99, v99
	v_pk_mul_f32 v[84:85], v[84:85], v[164:165] op_sel_hi:[1,0]
	v_pk_mul_f32 v[94:95], v[94:95], v[164:165] op_sel_hi:[1,0]
	v_pk_mul_f32 v[86:87], v[86:87], v[164:165] op_sel_hi:[1,0]
	v_add_f32_e32 v99, 1.0, v99
	v_rcp_f32_e32 v102, v99
	v_mul_f32_e32 v99, 0xbfb8aa3b, v113
	v_exp_f32_e32 v99, v99
	v_pk_mul_f32 v[88:89], v[88:89], v[164:165] op_sel_hi:[1,0]
	v_pk_mul_f32 v[90:91], v[90:91], v[164:165] op_sel_hi:[1,0]
	s_waitcnt lgkmcnt(0)
; __device__ __forceinline__ unsigned pk_bf16(float lo, float hi) { f32x2e v = {lo, hi}; bf16x2e b = __builtin_convertvector(v, bf16x2e); return __builtin_bit_cast(unsigned, b); }
; __device__ __forceinline__ float silu_mul(float g, float u) { return g * __builtin_amdgcn_rcpf(1.0f + __builtin_amdgcn_exp2f(-1.4426950408889634f * g)) * u; }
;     __device__ __forceinline__ void operator()(const f32x4 (&acc)[2][2][4][2], const Unit& u, int wr, int wc, int fr, int fq) const {
;     ...
;             for (int m = 0; m < 4; ++m) { bf16_t* rowp = O + (size_t)(row0 + ai * HALF + m * 16) * ldc + col0;
;                 const float rs = rsa[ai][m];
;                 const f32x4 g0 = acc[ai][0][m][0] * rs, g1 = acc[ai][0][m][1] * rs, u0 = acc[ai][1][m][0] * rs, u1 = acc[ai][1][m][1] * rs;
;                 u32x4 w; w.x = pk_bf16(silu_mul(g0[0], u0[0]), silu_mul(g0[1], u0[1])); w.y = pk_bf16(silu_mul(g0[2], u0[2]), silu_mul(g0[3], u0[3]));
;                 w.z = pk_bf16(silu_mul(g1[0], u1[0]), silu_mul(g1[1], u1[1])); w.w = pk_bf16(silu_mul(g1[2], u1[2]), silu_mul(g1[3], u1[3]));
;                 *(u32x4*)rowp = w; }
	v_pk_mul_f32 v[76:77], v[76:77], v[162:163] op_sel_hi:[1,0]
	v_add_f32_e32 v99, 1.0, v99
	v_rcp_f32_e32 v103, v99
	v_pk_mul_f32 v[68:69], v[68:69], v[162:163] op_sel_hi:[1,0]
	v_pk_mul_f32 v[78:79], v[78:79], v[162:163] op_sel_hi:[1,0]
	v_pk_mul_f32 v[70:71], v[70:71], v[162:163] op_sel_hi:[1,0]
	v_pk_mul_f32 v[102:103], v[112:113], v[102:103]
	v_pk_mul_f32 v[72:73], v[72:73], v[162:163] op_sel_hi:[1,0]
	v_pk_mul_f32 v[102:103], v[104:105], v[102:103]
	v_pk_mul_f32 v[74:75], v[74:75], v[162:163] op_sel_hi:[1,0]
	v_cvt_pk_bf16_f32 v99, v102, v103
	v_mul_f32_e32 v102, 0xbfb8aa3b, v106
	v_mul_f32_e32 v103, 0xbfb8aa3b, v107
	v_exp_f32_e32 v102, v102
	v_exp_f32_e32 v103, v103
	v_pk_mul_f32 v[60:61], v[60:61], v[148:149] op_sel_hi:[1,0]
	v_pk_mul_f32 v[52:53], v[52:53], v[148:149] op_sel_hi:[1,0]
	v_add_f32_e32 v102, 1.0, v102
	v_add_f32_e32 v103, 1.0, v103
	v_rcp_f32_e32 v102, v102
	v_rcp_f32_e32 v103, v103
	v_pk_mul_f32 v[62:63], v[62:63], v[148:149] op_sel_hi:[1,0]
	v_pk_mul_f32 v[54:55], v[54:55], v[148:149] op_sel_hi:[1,0]
	v_pk_mul_f32 v[56:57], v[56:57], v[148:149] op_sel_hi:[1,0]
	v_pk_mul_f32 v[102:103], v[106:107], v[102:103]
	v_pk_mul_f32 v[58:59], v[58:59], v[148:149] op_sel_hi:[1,0]
	v_pk_mul_f32 v[100:101], v[100:101], v[102:103]
	v_pk_mul_f32 v[44:45], v[44:45], v[146:147] op_sel_hi:[1,0]
	v_cvt_pk_bf16_f32 v100, v100, v101
	v_mul_f32_e32 v101, 0xbfb8aa3b, v108
	v_exp_f32_e32 v101, v101
	v_pk_mul_f32 v[36:37], v[36:37], v[146:147] op_sel_hi:[1,0]
	v_pk_mul_f32 v[46:47], v[46:47], v[146:147] op_sel_hi:[1,0]
	v_pk_mul_f32 v[38:39], v[38:39], v[146:147] op_sel_hi:[1,0]
	v_add_f32_e32 v101, 1.0, v101
	v_rcp_f32_e32 v102, v101
	v_mul_f32_e32 v101, 0xbfb8aa3b, v109
	v_exp_f32_e32 v101, v101
	v_pk_mul_f32 v[40:41], v[40:41], v[146:147] op_sel_hi:[1,0]
	v_pk_mul_f32 v[42:43], v[42:43], v[146:147] op_sel_hi:[1,0]
	v_pk_mul_f32 v[28:29], v[28:29], v[136:137] op_sel_hi:[1,0]
	v_add_f32_e32 v101, 1.0, v101
	v_rcp_f32_e32 v103, v101
	v_pk_mul_f32 v[20:21], v[20:21], v[136:137] op_sel_hi:[1,0]
	v_pk_mul_f32 v[30:31], v[30:31], v[136:137] op_sel_hi:[1,0]
	v_pk_mul_f32 v[22:23], v[22:23], v[136:137] op_sel_hi:[1,0]
	v_pk_mul_f32 v[102:103], v[108:109], v[102:103]
	v_pk_mul_f32 v[24:25], v[24:25], v[136:137] op_sel_hi:[1,0]
	v_pk_mul_f32 v[102:103], v[116:117], v[102:103]
	v_pk_mul_f32 v[26:27], v[26:27], v[136:137] op_sel_hi:[1,0]
	v_cvt_pk_bf16_f32 v101, v102, v103
	global_store_dwordx4 v[114:115], v[98:101], off
	v_pk_mul_f32 v[12:13], v[12:13], v[130:131] op_sel_hi:[1,0]
	v_pk_mul_f32 v[4:5], v[4:5], v[130:131] op_sel_hi:[1,0]
	v_pk_mul_f32 v[100:101], v[82:83], v[164:165] op_sel_hi:[1,0]
	v_pk_mul_f32 v[82:83], v[80:81], v[164:165] op_sel_hi:[1,0]
	v_mul_f32_e32 v80, 0xbfb8aa3b, v92
	v_mul_f32_e32 v81, 0xbfb8aa3b, v93
	v_exp_f32_e32 v80, v80
	v_exp_f32_e32 v81, v81
	v_or_b32_e32 v98, 32, v210
	v_mad_i64_i32 v[98:99], s[0:1], v98, s2, v[132:133]
	v_add_f32_e32 v80, 1.0, v80
	v_add_f32_e32 v81, 1.0, v81
	v_rcp_f32_e32 v80, v80
	v_rcp_f32_e32 v81, v81
	v_lshl_add_u64 v[98:99], v[98:99], 0, v[134:135]
	v_pk_mul_f32 v[14:15], v[14:15], v[130:131] op_sel_hi:[1,0]
	v_pk_mul_f32 v[6:7], v[6:7], v[130:131] op_sel_hi:[1,0]
	v_pk_mul_f32 v[80:81], v[92:93], v[80:81]
	v_pk_mul_f32 v[8:9], v[8:9], v[130:131] op_sel_hi:[1,0]
	v_pk_mul_f32 v[80:81], v[84:85], v[80:81]
	v_pk_mul_f32 v[10:11], v[10:11], v[130:131] op_sel_hi:[1,0]
	v_cvt_pk_bf16_f32 v80, v80, v81
	v_mul_f32_e32 v81, 0xbfb8aa3b, v94
	v_exp_f32_e32 v81, v81
	s_andn2_b64 vcc, exec, s[38:39]
	v_add_f32_e32 v81, 1.0, v81
	v_rcp_f32_e32 v84, v81
	v_mul_f32_e32 v81, 0xbfb8aa3b, v95
	v_exp_f32_e32 v81, v81
	s_nop 0
	v_add_f32_e32 v81, 1.0, v81
	v_rcp_f32_e32 v85, v81
	s_nop 0
	v_pk_mul_f32 v[84:85], v[94:95], v[84:85]
	s_nop 0
	v_pk_mul_f32 v[84:85], v[86:87], v[84:85]
	s_nop 0
	v_cvt_pk_bf16_f32 v81, v84, v85
	v_mul_f32_e32 v84, 0xbfb8aa3b, v88
	v_mul_f32_e32 v85, 0xbfb8aa3b, v89
	v_exp_f32_e32 v84, v84
	v_exp_f32_e32 v85, v85
	v_add_f32_e32 v84, 1.0, v84
	v_add_f32_e32 v85, 1.0, v85
	v_rcp_f32_e32 v84, v84
	v_rcp_f32_e32 v85, v85
	s_nop 0
	v_pk_mul_f32 v[84:85], v[88:89], v[84:85]
	s_nop 0
	v_pk_mul_f32 v[82:83], v[82:83], v[84:85]
	s_nop 0
	v_cvt_pk_bf16_f32 v82, v82, v83
	v_mul_f32_e32 v83, 0xbfb8aa3b, v90
	v_exp_f32_e32 v83, v83
	s_nop 0
	v_add_f32_e32 v83, 1.0, v83
	v_rcp_f32_e32 v84, v83
	v_mul_f32_e32 v83, 0xbfb8aa3b, v91
	v_exp_f32_e32 v83, v83
	s_nop 0
	v_add_f32_e32 v83, 1.0, v83
	v_rcp_f32_e32 v85, v83
	s_nop 0
	v_pk_mul_f32 v[84:85], v[90:91], v[84:85]
	s_nop 0
	v_pk_mul_f32 v[84:85], v[100:101], v[84:85]
	s_nop 0
	v_cvt_pk_bf16_f32 v83, v84, v85
	global_store_dwordx4 v[98:99], v[80:83], off
	s_nop 1
	v_pk_mul_f32 v[82:83], v[66:67], v[162:163] op_sel_hi:[1,0]
	v_pk_mul_f32 v[66:67], v[64:65], v[162:163] op_sel_hi:[1,0]
	v_mul_f32_e32 v64, 0xbfb8aa3b, v76
	v_mul_f32_e32 v65, 0xbfb8aa3b, v77
	v_exp_f32_e32 v64, v64
	v_exp_f32_e32 v65, v65
	v_or_b32_e32 v80, 48, v210
	v_mad_i64_i32 v[80:81], s[0:1], v80, s2, v[132:133]
	v_add_f32_e32 v64, 1.0, v64
	v_add_f32_e32 v65, 1.0, v65
	v_rcp_f32_e32 v64, v64
	v_rcp_f32_e32 v65, v65
	v_lshl_add_u64 v[80:81], v[80:81], 0, v[134:135]
	v_pk_mul_f32 v[64:65], v[76:77], v[64:65]
	s_nop 0
	v_pk_mul_f32 v[64:65], v[68:69], v[64:65]
	s_nop 0
	v_cvt_pk_bf16_f32 v64, v64, v65
	v_mul_f32_e32 v65, 0xbfb8aa3b, v78
	v_exp_f32_e32 v65, v65
	s_nop 0
	v_add_f32_e32 v65, 1.0, v65
	v_rcp_f32_e32 v68, v65
	v_mul_f32_e32 v65, 0xbfb8aa3b, v79
	v_exp_f32_e32 v65, v65
	s_nop 0
	v_add_f32_e32 v65, 1.0, v65
	v_rcp_f32_e32 v69, v65
	s_nop 0
	v_pk_mul_f32 v[68:69], v[78:79], v[68:69]
	s_nop 0
	v_pk_mul_f32 v[68:69], v[70:71], v[68:69]
	s_nop 0
	v_cvt_pk_bf16_f32 v65, v68, v69
; __device__ __forceinline__ unsigned pk_bf16(float lo, float hi) { f32x2e v = {lo, hi}; bf16x2e b = __builtin_convertvector(v, bf16x2e); return __builtin_bit_cast(unsigned, b); }
; __device__ __forceinline__ float silu_mul(float g, float u) { return g * __builtin_amdgcn_rcpf(1.0f + __builtin_amdgcn_exp2f(-1.4426950408889634f * g)) * u; }
;     __device__ __forceinline__ void operator()(const f32x4 (&acc)[2][2][4][2], const Unit& u, int wr, int wc, int fr, int fq) const {
;     ...
;             for (int m = 0; m < 4; ++m) { bf16_t* rowp = O + (size_t)(row0 + ai * HALF + m * 16) * ldc + col0;
;                 const float rs = rsa[ai][m];
;                 const f32x4 g0 = acc[ai][0][m][0] * rs, g1 = acc[ai][0][m][1] * rs, u0 = acc[ai][1][m][0] * rs, u1 = acc[ai][1][m][1] * rs;
;                 u32x4 w; w.x = pk_bf16(silu_mul(g0[0], u0[0]), silu_mul(g0[1], u0[1])); w.y = pk_bf16(silu_mul(g0[2], u0[2]), silu_mul(g0[3], u0[3]));
;                 w.z = pk_bf16(silu_mul(g1[0], u1[0]), silu_mul(g1[1], u1[1])); w.w = pk_bf16(silu_mul(g1[2], u1[2]), silu_mul(g1[3], u1[3]));
;                 *(u32x4*)rowp = w; }
	v_mul_f32_e32 v68, 0xbfb8aa3b, v72
	v_mul_f32_e32 v69, 0xbfb8aa3b, v73
	v_exp_f32_e32 v68, v68
	v_exp_f32_e32 v69, v69
	v_add_f32_e32 v68, 1.0, v68
	v_add_f32_e32 v69, 1.0, v69
	v_rcp_f32_e32 v68, v68
	v_rcp_f32_e32 v69, v69
	s_nop 0
	v_pk_mul_f32 v[68:69], v[72:73], v[68:69]
	s_nop 0
	v_pk_mul_f32 v[66:67], v[66:67], v[68:69]
	s_nop 0
	v_cvt_pk_bf16_f32 v66, v66, v67
	v_mul_f32_e32 v67, 0xbfb8aa3b, v74
	v_exp_f32_e32 v67, v67
	s_nop 0
	v_add_f32_e32 v67, 1.0, v67
	v_rcp_f32_e32 v68, v67
	v_mul_f32_e32 v67, 0xbfb8aa3b, v75
	v_exp_f32_e32 v67, v67
	s_nop 0
	v_add_f32_e32 v67, 1.0, v67
	v_rcp_f32_e32 v69, v67
	s_nop 0
	v_pk_mul_f32 v[68:69], v[74:75], v[68:69]
	s_nop 0
	v_pk_mul_f32 v[68:69], v[82:83], v[68:69]
	s_nop 0
	v_cvt_pk_bf16_f32 v67, v68, v69
	global_store_dwordx4 v[80:81], v[64:67], off
	s_nop 1
	v_pk_mul_f32 v[66:67], v[50:51], v[148:149] op_sel_hi:[1,0]
	v_pk_mul_f32 v[50:51], v[48:49], v[148:149] op_sel_hi:[1,0]
	v_mul_f32_e32 v48, 0xbfb8aa3b, v60
	v_mul_f32_e32 v49, 0xbfb8aa3b, v61
	v_exp_f32_e32 v48, v48
	v_exp_f32_e32 v49, v49
	v_add_u32_e32 v64, 0x80, v210
	v_mad_i64_i32 v[64:65], s[0:1], v64, s2, v[132:133]
	v_add_f32_e32 v48, 1.0, v48
	v_add_f32_e32 v49, 1.0, v49
	v_rcp_f32_e32 v48, v48
	v_rcp_f32_e32 v49, v49
	v_lshl_add_u64 v[64:65], v[64:65], 0, v[134:135]
	v_pk_mul_f32 v[48:49], v[60:61], v[48:49]
	s_nop 0
	v_pk_mul_f32 v[48:49], v[52:53], v[48:49]
	s_nop 0
	v_cvt_pk_bf16_f32 v48, v48, v49
	v_mul_f32_e32 v49, 0xbfb8aa3b, v62
	v_exp_f32_e32 v49, v49
	s_nop 0
	v_add_f32_e32 v49, 1.0, v49
	v_rcp_f32_e32 v52, v49
	v_mul_f32_e32 v49, 0xbfb8aa3b, v63
	v_exp_f32_e32 v49, v49
	s_nop 0
	v_add_f32_e32 v49, 1.0, v49
	v_rcp_f32_e32 v53, v49
	s_nop 0
	v_pk_mul_f32 v[52:53], v[62:63], v[52:53]
	s_nop 0
	v_pk_mul_f32 v[52:53], v[54:55], v[52:53]
	s_nop 0
	v_cvt_pk_bf16_f32 v49, v52, v53
	v_mul_f32_e32 v52, 0xbfb8aa3b, v56
	v_mul_f32_e32 v53, 0xbfb8aa3b, v57
	v_exp_f32_e32 v52, v52
	v_exp_f32_e32 v53, v53
	v_add_f32_e32 v52, 1.0, v52
	v_add_f32_e32 v53, 1.0, v53
	v_rcp_f32_e32 v52, v52
	v_rcp_f32_e32 v53, v53
	s_nop 0
	v_pk_mul_f32 v[52:53], v[56:57], v[52:53]
	s_nop 0
	v_pk_mul_f32 v[50:51], v[50:51], v[52:53]
	s_nop 0
	v_cvt_pk_bf16_f32 v50, v50, v51
	v_mul_f32_e32 v51, 0xbfb8aa3b, v58
	v_exp_f32_e32 v51, v51
	s_nop 0
	v_add_f32_e32 v51, 1.0, v51
	v_rcp_f32_e32 v52, v51
	v_mul_f32_e32 v51, 0xbfb8aa3b, v59
	v_exp_f32_e32 v51, v51
	s_nop 0
	v_add_f32_e32 v51, 1.0, v51
	v_rcp_f32_e32 v53, v51
	s_nop 0
	v_pk_mul_f32 v[52:53], v[58:59], v[52:53]
	s_nop 0
	v_pk_mul_f32 v[52:53], v[66:67], v[52:53]
	s_nop 0
	v_cvt_pk_bf16_f32 v51, v52, v53
	global_store_dwordx4 v[64:65], v[48:51], off
	s_nop 1
	v_pk_mul_f32 v[50:51], v[34:35], v[146:147] op_sel_hi:[1,0]
	v_pk_mul_f32 v[34:35], v[32:33], v[146:147] op_sel_hi:[1,0]
	v_mul_f32_e32 v32, 0xbfb8aa3b, v44
	v_mul_f32_e32 v33, 0xbfb8aa3b, v45
	v_exp_f32_e32 v32, v32
	v_exp_f32_e32 v33, v33
	v_add_u32_e32 v48, 0x90, v210
	v_mad_i64_i32 v[48:49], s[0:1], v48, s2, v[132:133]
	v_add_f32_e32 v32, 1.0, v32
	v_add_f32_e32 v33, 1.0, v33
	v_rcp_f32_e32 v32, v32
	v_rcp_f32_e32 v33, v33
	v_lshl_add_u64 v[48:49], v[48:49], 0, v[134:135]
	v_pk_mul_f32 v[32:33], v[44:45], v[32:33]
	s_nop 0
	v_pk_mul_f32 v[32:33], v[36:37], v[32:33]
	s_nop 0
	v_cvt_pk_bf16_f32 v32, v32, v33
	v_mul_f32_e32 v33, 0xbfb8aa3b, v46
	v_exp_f32_e32 v33, v33
	s_nop 0
	v_add_f32_e32 v33, 1.0, v33
	v_rcp_f32_e32 v36, v33
	v_mul_f32_e32 v33, 0xbfb8aa3b, v47
	v_exp_f32_e32 v33, v33
	s_nop 0
	v_add_f32_e32 v33, 1.0, v33
	v_rcp_f32_e32 v37, v33
	s_nop 0
	v_pk_mul_f32 v[36:37], v[46:47], v[36:37]
	s_nop 0
	v_pk_mul_f32 v[36:37], v[38:39], v[36:37]
	s_nop 0
	v_cvt_pk_bf16_f32 v33, v36, v37
	v_mul_f32_e32 v36, 0xbfb8aa3b, v40
	v_mul_f32_e32 v37, 0xbfb8aa3b, v41
	v_exp_f32_e32 v36, v36
	v_exp_f32_e32 v37, v37
	v_add_f32_e32 v36, 1.0, v36
	v_add_f32_e32 v37, 1.0, v37
	v_rcp_f32_e32 v36, v36
	v_rcp_f32_e32 v37, v37
	s_nop 0
	v_pk_mul_f32 v[36:37], v[40:41], v[36:37]
	s_nop 0
	v_pk_mul_f32 v[34:35], v[34:35], v[36:37]
	s_nop 0
	v_cvt_pk_bf16_f32 v34, v34, v35
; __device__ __forceinline__ unsigned pk_bf16(float lo, float hi) { f32x2e v = {lo, hi}; bf16x2e b = __builtin_convertvector(v, bf16x2e); return __builtin_bit_cast(unsigned, b); }
; __device__ __forceinline__ float silu_mul(float g, float u) { return g * __builtin_amdgcn_rcpf(1.0f + __builtin_amdgcn_exp2f(-1.4426950408889634f * g)) * u; }
;     __device__ __forceinline__ void operator()(const f32x4 (&acc)[2][2][4][2], const Unit& u, int wr, int wc, int fr, int fq) const {
;     ...
;             for (int m = 0; m < 4; ++m) { bf16_t* rowp = O + (size_t)(row0 + ai * HALF + m * 16) * ldc + col0;
;                 const float rs = rsa[ai][m];
;                 const f32x4 g0 = acc[ai][0][m][0] * rs, g1 = acc[ai][0][m][1] * rs, u0 = acc[ai][1][m][0] * rs, u1 = acc[ai][1][m][1] * rs;
;                 u32x4 w; w.x = pk_bf16(silu_mul(g0[0], u0[0]), silu_mul(g0[1], u0[1])); w.y = pk_bf16(silu_mul(g0[2], u0[2]), silu_mul(g0[3], u0[3]));
;                 w.z = pk_bf16(silu_mul(g1[0], u1[0]), silu_mul(g1[1], u1[1])); w.w = pk_bf16(silu_mul(g1[2], u1[2]), silu_mul(g1[3], u1[3]));
;                 *(u32x4*)rowp = w; }
	v_mul_f32_e32 v35, 0xbfb8aa3b, v42
	v_exp_f32_e32 v35, v35
	s_nop 0
	v_add_f32_e32 v35, 1.0, v35
	v_rcp_f32_e32 v36, v35
	v_mul_f32_e32 v35, 0xbfb8aa3b, v43
	v_exp_f32_e32 v35, v35
	s_nop 0
	v_add_f32_e32 v35, 1.0, v35
	v_rcp_f32_e32 v37, v35
	s_nop 0
	v_pk_mul_f32 v[36:37], v[42:43], v[36:37]
	s_nop 0
	v_pk_mul_f32 v[36:37], v[50:51], v[36:37]
	s_nop 0
	v_cvt_pk_bf16_f32 v35, v36, v37
	global_store_dwordx4 v[48:49], v[32:35], off
	s_nop 1
	v_pk_mul_f32 v[34:35], v[18:19], v[136:137] op_sel_hi:[1,0]
	v_pk_mul_f32 v[18:19], v[16:17], v[136:137] op_sel_hi:[1,0]
	v_mul_f32_e32 v16, 0xbfb8aa3b, v28
	v_mul_f32_e32 v17, 0xbfb8aa3b, v29
	v_exp_f32_e32 v16, v16
	v_exp_f32_e32 v17, v17
	v_add_u32_e32 v32, 0xa0, v210
	v_mad_i64_i32 v[32:33], s[0:1], v32, s2, v[132:133]
	v_add_f32_e32 v16, 1.0, v16
	v_add_f32_e32 v17, 1.0, v17
	v_rcp_f32_e32 v16, v16
	v_rcp_f32_e32 v17, v17
	v_lshl_add_u64 v[32:33], v[32:33], 0, v[134:135]
	v_pk_mul_f32 v[16:17], v[28:29], v[16:17]
	s_nop 0
	v_pk_mul_f32 v[16:17], v[20:21], v[16:17]
	s_nop 0
	v_cvt_pk_bf16_f32 v16, v16, v17
	v_mul_f32_e32 v17, 0xbfb8aa3b, v30
	v_exp_f32_e32 v17, v17
	s_nop 0
	v_add_f32_e32 v17, 1.0, v17
	v_rcp_f32_e32 v20, v17
	v_mul_f32_e32 v17, 0xbfb8aa3b, v31
	v_exp_f32_e32 v17, v17
	s_nop 0
	v_add_f32_e32 v17, 1.0, v17
	v_rcp_f32_e32 v21, v17
	s_nop 0
	v_pk_mul_f32 v[20:21], v[30:31], v[20:21]
	s_nop 0
	v_pk_mul_f32 v[20:21], v[22:23], v[20:21]
	s_nop 0
	v_cvt_pk_bf16_f32 v17, v20, v21
	v_mul_f32_e32 v20, 0xbfb8aa3b, v24
	v_mul_f32_e32 v21, 0xbfb8aa3b, v25
	v_exp_f32_e32 v20, v20
	v_exp_f32_e32 v21, v21
	v_add_f32_e32 v20, 1.0, v20
	v_add_f32_e32 v21, 1.0, v21
	v_rcp_f32_e32 v20, v20
	v_rcp_f32_e32 v21, v21
	s_nop 0
	v_pk_mul_f32 v[20:21], v[24:25], v[20:21]
	s_nop 0
	v_pk_mul_f32 v[18:19], v[18:19], v[20:21]
	s_nop 0
	v_cvt_pk_bf16_f32 v18, v18, v19
	v_mul_f32_e32 v19, 0xbfb8aa3b, v26
	v_exp_f32_e32 v19, v19
	s_nop 0
	v_add_f32_e32 v19, 1.0, v19
	v_rcp_f32_e32 v20, v19
	v_mul_f32_e32 v19, 0xbfb8aa3b, v27
	v_exp_f32_e32 v19, v19
	s_nop 0
	v_add_f32_e32 v19, 1.0, v19
	v_rcp_f32_e32 v21, v19
	s_nop 0
	v_pk_mul_f32 v[20:21], v[26:27], v[20:21]
	s_nop 0
	v_pk_mul_f32 v[20:21], v[34:35], v[20:21]
	s_nop 0
	v_cvt_pk_bf16_f32 v19, v20, v21
	global_store_dwordx4 v[32:33], v[16:19], off
	s_nop 1
	v_pk_mul_f32 v[18:19], v[2:3], v[130:131] op_sel_hi:[1,0]
	v_pk_mul_f32 v[2:3], v[0:1], v[130:131] op_sel_hi:[1,0]
	v_mul_f32_e32 v0, 0xbfb8aa3b, v12
	v_mul_f32_e32 v1, 0xbfb8aa3b, v13
	v_exp_f32_e32 v0, v0
	v_exp_f32_e32 v1, v1
	v_add_u32_e32 v16, 0xb0, v210
	v_mad_i64_i32 v[16:17], s[0:1], v16, s2, v[132:133]
	v_add_f32_e32 v0, 1.0, v0
	v_add_f32_e32 v1, 1.0, v1
	v_rcp_f32_e32 v0, v0
	v_rcp_f32_e32 v1, v1
	v_lshl_add_u64 v[16:17], v[16:17], 0, v[134:135]
	s_mov_b64 s[0:1], -1
	v_pk_mul_f32 v[0:1], v[12:13], v[0:1]
	s_nop 0
	v_pk_mul_f32 v[0:1], v[4:5], v[0:1]
	s_nop 0
	v_cvt_pk_bf16_f32 v0, v0, v1
	v_mul_f32_e32 v1, 0xbfb8aa3b, v14
	v_exp_f32_e32 v1, v1
	s_nop 0
	v_add_f32_e32 v1, 1.0, v1
	v_rcp_f32_e32 v4, v1
	v_mul_f32_e32 v1, 0xbfb8aa3b, v15
	v_exp_f32_e32 v1, v1
	s_nop 0
	v_add_f32_e32 v1, 1.0, v1
	v_rcp_f32_e32 v5, v1
	s_nop 0
	v_pk_mul_f32 v[4:5], v[14:15], v[4:5]
	s_nop 0
	v_pk_mul_f32 v[4:5], v[6:7], v[4:5]
	s_nop 0
	v_cvt_pk_bf16_f32 v1, v4, v5
	v_mul_f32_e32 v4, 0xbfb8aa3b, v8
	v_mul_f32_e32 v5, 0xbfb8aa3b, v9
	v_exp_f32_e32 v4, v4
	v_exp_f32_e32 v5, v5
	v_add_f32_e32 v4, 1.0, v4
	v_add_f32_e32 v5, 1.0, v5
	v_rcp_f32_e32 v4, v4
	v_rcp_f32_e32 v5, v5
	s_nop 0
	v_pk_mul_f32 v[4:5], v[8:9], v[4:5]
	s_nop 0
	v_pk_mul_f32 v[2:3], v[2:3], v[4:5]
	s_nop 0
	v_cvt_pk_bf16_f32 v2, v2, v3
	v_mul_f32_e32 v3, 0xbfb8aa3b, v10
	v_exp_f32_e32 v3, v3
	s_nop 0
	v_add_f32_e32 v3, 1.0, v3
	v_rcp_f32_e32 v4, v3
	v_mul_f32_e32 v3, 0xbfb8aa3b, v11
	v_exp_f32_e32 v3, v3
	s_nop 0
	v_add_f32_e32 v3, 1.0, v3
	v_rcp_f32_e32 v5, v3
	s_nop 0
	v_pk_mul_f32 v[4:5], v[10:11], v[4:5]
	s_nop 0
	v_pk_mul_f32 v[4:5], v[18:19], v[4:5]
	s_nop 0
	v_cvt_pk_bf16_f32 v3, v4, v5
	global_store_dwordx4 v[16:17], v[0:3], off
	s_branch .Lswi_join
